# baseline (speedup 1.0000x reference)
; #define MFMA16(a, b, c) __builtin_amdgcn_mfma_f32_16x16x32_bf16((a), (b), (c), 0, 0, 0)
; static __device__ __forceinline__ void attn_item(const Params& p, int head, int j, char* smraw) {
;     ...
;     bf16x8 pf[2][2];
; #pragma unroll
;     for (int qt = 0; qt < 2; ++qt) {
;       float ps = 0.f;
; #pragma unroll
;       for (int kt = 0; kt < 4; ++kt)
; #pragma unroll
;         for (int r = 0; r < 4; ++r) {
;           const float pv = __builtin_amdgcn_exp2f(sacc[kt][qt][r]);
;           sacc[kt][qt][r] = pv; ps += pv;
;         }
;       lrun[qt] += ps;
; #pragma unroll
;       for (int k2 = 0; k2 < 2; ++k2) {
;         u32x4 pk = {cvtpk(sacc[2 * k2][qt][0], sacc[2 * k2][qt][1]), cvtpk(sacc[2 * k2][qt][2], sacc[2 * k2][qt][3]),
;                     cvtpk(sacc[2 * k2 + 1][qt][0], sacc[2 * k2 + 1][qt][1]), cvtpk(sacc[2 * k2 + 1][qt][2], sacc[2 * k2 + 1][qt][3])};
;         pf[qt][k2] = *(bf16x8*)&pk;
;       }
;     }
;     {
;       bf16x8 vf[2][4];
; #pragma unroll
;       for (int k2 = 0; k2 < 2; ++k2)
; #pragma unroll
;         for (int dt = 0; dt < 4; ++dt) vf[k2][dt] = *(const bf16x8*)(cV + (dt * 16 + l15) * 64 + (((k2 * 4 + quad) ^ (l15 & 7)) << 3));
;       __builtin_amdgcn_sched_barrier(0);
;       __builtin_amdgcn_s_setprio(1);
; #pragma unroll
;       for (int k2 = 0; k2 < 2; ++k2)
; #pragma unroll
;         for (int dt = 0; dt < 4; ++dt)
; #pragma unroll
;           for (int qt = 0; qt < 2; ++qt) oacc[dt][qt] = MFMA16(vf[k2][dt], pf[qt][k2], oacc[dt][qt]);
;       __builtin_amdgcn_s_setprio(0);
;       __builtin_amdgcn_sched_barrier(0);
;     }
.LBB0_380:
	v_exp_f32_e32 v173, v124
	v_exp_f32_e32 v169, v126
	v_exp_f32_e32 v161, v122
	v_exp_f32_e32 v172, v108
	v_exp_f32_e32 v170, v109
	v_exp_f32_e32 v168, v110
	v_exp_f32_e32 v166, v111
	v_exp_f32_e32 v164, v104
	v_exp_f32_e32 v162, v105
	v_exp_f32_e32 v160, v106
	v_exp_f32_e32 v158, v107
	v_exp_f32_e32 v156, v100
	v_exp_f32_e32 v126, v101
	v_exp_f32_e32 v124, v102
	v_exp_f32_e32 v122, v103
	ds_read_b128 v[100:103], v187 offset:16384
	ds_read_b128 v[104:107], v187 offset:18432
	ds_read_b128 v[108:111], v187 offset:20480
	ds_read_b128 v[200:203], v187 offset:22528
	ds_read_b128 v[204:207], v188 offset:16384
	ds_read_b128 v[208:211], v188 offset:18432
	ds_read_b128 v[212:215], v188 offset:20480
	ds_read_b128 v[216:219], v188 offset:22528
	v_exp_f32_e32 v171, v125
	v_exp_f32_e32 v167, v127
	v_exp_f32_e32 v165, v120
	v_exp_f32_e32 v163, v121
	v_exp_f32_e32 v159, v123
	v_exp_f32_e32 v157, v116
	v_exp_f32_e32 v127, v117
	v_exp_f32_e32 v125, v118
	v_exp_f32_e32 v123, v119
	v_exp_f32_e32 v121, v112
	v_exp_f32_e32 v119, v113
	v_exp_f32_e32 v117, v114
	v_exp_f32_e32 v113, v115
	v_exp_f32_e32 v120, v96
	v_exp_f32_e32 v118, v97
	v_exp_f32_e32 v116, v98
	v_exp_f32_e32 v112, v99
	v_cvt_pk_bf16_f32 v192, v173, v171
	v_cvt_pk_bf16_f32 v193, v169, v167
	v_cvt_pk_bf16_f32 v194, v165, v163
	v_cvt_pk_bf16_f32 v195, v161, v159
	v_cvt_pk_bf16_f32 v196, v157, v127
	v_cvt_pk_bf16_f32 v197, v125, v123
	v_cvt_pk_bf16_f32 v198, v121, v119
	v_cvt_pk_bf16_f32 v199, v117, v113
	v_cvt_pk_bf16_f32 v96, v172, v170
	v_cvt_pk_bf16_f32 v97, v168, v166
	v_cvt_pk_bf16_f32 v98, v164, v162
	v_cvt_pk_bf16_f32 v99, v160, v158
	v_cvt_pk_bf16_f32 v220, v156, v126
	v_cvt_pk_bf16_f32 v221, v124, v122
	v_cvt_pk_bf16_f32 v222, v120, v118
	v_cvt_pk_bf16_f32 v223, v116, v112
	s_setprio 1
	s_waitcnt lgkmcnt(7)
	v_mfma_f32_16x16x32_bf16 v[92:95], v[100:103], v[192:195], v[92:95]
	v_mfma_f32_16x16x32_bf16 v[76:79], v[100:103], v[96:99], v[76:79]
	v_pk_add_f32 v[226:227], v[170:171], v[172:173]
	s_waitcnt lgkmcnt(6)
	v_mfma_f32_16x16x32_bf16 v[100:103], v[104:107], v[192:195], v[88:91]
	v_pk_add_f32 v[226:227], v[168:169], v[226:227]
	v_mfma_f32_16x16x32_bf16 v[72:75], v[104:107], v[96:99], v[72:75]
	v_pk_add_f32 v[226:227], v[166:167], v[226:227]
	s_waitcnt lgkmcnt(5)
	v_mfma_f32_16x16x32_bf16 v[104:107], v[108:111], v[192:195], v[84:87]
	v_pk_add_f32 v[226:227], v[164:165], v[226:227]
	v_mfma_f32_16x16x32_bf16 v[68:71], v[108:111], v[96:99], v[68:71]
	v_pk_add_f32 v[226:227], v[162:163], v[226:227]
	s_waitcnt lgkmcnt(4)
	v_mfma_f32_16x16x32_bf16 v[108:111], v[200:203], v[192:195], v[80:83]
	v_pk_add_f32 v[226:227], v[160:161], v[226:227]
	v_mfma_f32_16x16x32_bf16 v[64:67], v[200:203], v[96:99], v[64:67]
	v_pk_add_f32 v[226:227], v[158:159], v[226:227]
	s_waitcnt lgkmcnt(3)
	v_mfma_f32_16x16x32_bf16 v[92:95], v[204:207], v[196:199], v[92:95]
	v_pk_add_f32 v[226:227], v[156:157], v[226:227]
	v_mfma_f32_16x16x32_bf16 v[88:91], v[204:207], v[220:223], v[76:79]
	v_pk_add_f32 v[226:227], v[126:127], v[226:227]
	s_waitcnt lgkmcnt(2)
	v_mfma_f32_16x16x32_bf16 v[84:87], v[208:211], v[196:199], v[100:103]
	v_pk_add_f32 v[226:227], v[124:125], v[226:227]
	v_mfma_f32_16x16x32_bf16 v[80:83], v[208:211], v[220:223], v[72:75]
	v_pk_add_f32 v[226:227], v[122:123], v[226:227]
	s_waitcnt lgkmcnt(1)
	v_mfma_f32_16x16x32_bf16 v[76:79], v[212:215], v[196:199], v[104:107]
	v_pk_add_f32 v[226:227], v[120:121], v[226:227]
	v_mfma_f32_16x16x32_bf16 v[72:75], v[212:215], v[220:223], v[68:71]
	v_pk_add_f32 v[226:227], v[118:119], v[226:227]
	s_waitcnt lgkmcnt(0)
	v_mfma_f32_16x16x32_bf16 v[68:71], v[216:219], v[196:199], v[108:111]
	v_pk_add_f32 v[226:227], v[116:117], v[226:227]
	v_mfma_f32_16x16x32_bf16 v[64:67], v[216:219], v[220:223], v[64:67]
	v_pk_add_f32 v[226:227], v[112:113], v[226:227]
	s_setprio 0
	v_pk_add_f32 v[144:145], v[144:145], v[226:227]
	s_cmp_ge_u32 s3, s2
	s_waitcnt vmcnt(4)
	ds_write_b128 v179, v[44:47] offset:24576
	s_waitcnt vmcnt(3)
	ds_write_b128 v180, v[48:51] offset:24576
	s_waitcnt vmcnt(2)
	ds_write_b128 v181, v[52:55] offset:24576
	s_waitcnt vmcnt(1)
	ds_write_b128 v182, v[56:59] offset:40960
	s_waitcnt vmcnt(0)
	ds_write_b128 v183, v[60:63] offset:40960
	s_waitcnt lgkmcnt(0)
	s_barrier
	s_cbranch_scc1 .LBB0_382
	v_lshl_add_u64 v[44:45], v[142:143], 0, s[98:99]
	v_lshl_add_u64 v[48:49], v[140:141], 0, s[98:99]
	v_lshl_add_u64 v[52:53], v[138:139], 0, s[98:99]
	global_load_dwordx4 v[44:47], v[44:45], off
	s_nop 0
	global_load_dwordx4 v[48:51], v[48:49], off
	s_nop 0
	global_load_dwordx4 v[52:55], v[52:53], off
	global_load_dwordx4 v[56:59], v[134:135], off offset:384
	global_load_dwordx4 v[60:63], v[136:137], off offset:384

; #define MFMA16(a, b, c) __builtin_amdgcn_mfma_f32_16x16x32_bf16((a), (b), (c), 0, 0, 0)
; static __device__ __forceinline__ void attn_item(const Params& p, int head, int j, char* smraw) {
;     ...
;     bf16x8 pf[2][2];
; #pragma unroll
;     for (int qt = 0; qt < 2; ++qt) {
;       float ps = 0.f;
; #pragma unroll
;       for (int kt = 0; kt < 4; ++kt)
; #pragma unroll
;         for (int r = 0; r < 4; ++r) {
;           const float pv = __builtin_amdgcn_exp2f(sacc[kt][qt][r]);
;           sacc[kt][qt][r] = pv; ps += pv;
;         }
;       lrun[qt] += ps;
; #pragma unroll
;       for (int k2 = 0; k2 < 2; ++k2) {
;         u32x4 pk = {cvtpk(sacc[2 * k2][qt][0], sacc[2 * k2][qt][1]), cvtpk(sacc[2 * k2][qt][2], sacc[2 * k2][qt][3]),
;                     cvtpk(sacc[2 * k2 + 1][qt][0], sacc[2 * k2 + 1][qt][1]), cvtpk(sacc[2 * k2 + 1][qt][2], sacc[2 * k2 + 1][qt][3])};
;         pf[qt][k2] = *(bf16x8*)&pk;
;       }
;     }
;     {
;       bf16x8 vf[2][4];
; #pragma unroll
;       for (int k2 = 0; k2 < 2; ++k2)
; #pragma unroll
;         for (int dt = 0; dt < 4; ++dt) vf[k2][dt] = *(const bf16x8*)(cV + (dt * 16 + l15) * 64 + (((k2 * 4 + quad) ^ (l15 & 7)) << 3));
;       __builtin_amdgcn_sched_barrier(0);
;       __builtin_amdgcn_s_setprio(1);
; #pragma unroll
;       for (int k2 = 0; k2 < 2; ++k2)
; #pragma unroll
;         for (int dt = 0; dt < 4; ++dt)
; #pragma unroll
;           for (int qt = 0; qt < 2; ++qt) oacc[dt][qt] = MFMA16(vf[k2][dt], pf[qt][k2], oacc[dt][qt]);
;       __builtin_amdgcn_s_setprio(0);
;       __builtin_amdgcn_sched_barrier(0);
;     }
.LBB0_384:
	v_exp_f32_e32 v163, v124
	v_exp_f32_e32 v159, v126
	v_exp_f32_e32 v151, v122
	v_exp_f32_e32 v162, v108
	v_exp_f32_e32 v160, v109
	v_exp_f32_e32 v158, v110
	v_exp_f32_e32 v156, v111
	v_exp_f32_e32 v154, v104
	v_exp_f32_e32 v152, v105
	v_exp_f32_e32 v150, v106
	v_exp_f32_e32 v148, v107
	v_exp_f32_e32 v146, v100
	v_exp_f32_e32 v126, v101
	v_exp_f32_e32 v124, v102
	v_exp_f32_e32 v122, v103
	ds_read_b128 v[100:103], v187 offset:40960
	ds_read_b128 v[104:107], v187 offset:43008
	ds_read_b128 v[108:111], v187 offset:45056
	ds_read_b128 v[192:195], v187 offset:47104
	ds_read_b128 v[196:199], v188 offset:40960
	ds_read_b128 v[200:203], v188 offset:43008
	ds_read_b128 v[204:207], v188 offset:45056
	ds_read_b128 v[208:211], v188 offset:47104
	v_exp_f32_e32 v161, v125
	v_exp_f32_e32 v157, v127
	v_exp_f32_e32 v155, v120
	v_exp_f32_e32 v153, v121
	v_exp_f32_e32 v149, v123
	v_exp_f32_e32 v147, v116
	v_exp_f32_e32 v127, v117
	v_exp_f32_e32 v125, v118
	v_exp_f32_e32 v123, v119
	v_exp_f32_e32 v121, v112
	v_exp_f32_e32 v119, v113
	v_exp_f32_e32 v117, v114
	v_exp_f32_e32 v113, v115
	v_exp_f32_e32 v120, v96
	v_exp_f32_e32 v118, v97
	v_exp_f32_e32 v116, v98
	v_exp_f32_e32 v112, v99
	v_cvt_pk_bf16_f32 v164, v163, v161
	v_cvt_pk_bf16_f32 v165, v159, v157
	v_cvt_pk_bf16_f32 v166, v155, v153
	v_cvt_pk_bf16_f32 v167, v151, v149
	v_cvt_pk_bf16_f32 v168, v147, v127
	v_cvt_pk_bf16_f32 v169, v125, v123
	v_cvt_pk_bf16_f32 v170, v121, v119
	v_cvt_pk_bf16_f32 v171, v117, v113
	v_cvt_pk_bf16_f32 v96, v162, v160
	v_cvt_pk_bf16_f32 v97, v158, v156
	v_cvt_pk_bf16_f32 v98, v154, v152
	v_cvt_pk_bf16_f32 v99, v150, v148
	v_cvt_pk_bf16_f32 v212, v146, v126
	v_cvt_pk_bf16_f32 v213, v124, v122
	v_cvt_pk_bf16_f32 v214, v120, v118
	v_cvt_pk_bf16_f32 v215, v116, v112
	s_setprio 1
	s_waitcnt lgkmcnt(7)
	v_mfma_f32_16x16x32_bf16 v[92:95], v[100:103], v[164:167], v[92:95]
	v_mfma_f32_16x16x32_bf16 v[88:91], v[100:103], v[96:99], v[88:91]
	v_pk_add_f32 v[226:227], v[160:161], v[162:163]
	s_waitcnt lgkmcnt(6)
	v_mfma_f32_16x16x32_bf16 v[84:87], v[104:107], v[164:167], v[84:87]
	v_pk_add_f32 v[226:227], v[158:159], v[226:227]
	v_mfma_f32_16x16x32_bf16 v[80:83], v[104:107], v[96:99], v[80:83]
	v_pk_add_f32 v[226:227], v[156:157], v[226:227]
	s_waitcnt lgkmcnt(5)
	v_mfma_f32_16x16x32_bf16 v[100:103], v[108:111], v[164:167], v[76:79]
	v_pk_add_f32 v[226:227], v[154:155], v[226:227]
	v_mfma_f32_16x16x32_bf16 v[104:107], v[108:111], v[96:99], v[72:75]
	v_pk_add_f32 v[226:227], v[152:153], v[226:227]
	s_waitcnt lgkmcnt(4)
	v_mfma_f32_16x16x32_bf16 v[108:111], v[192:195], v[164:167], v[68:71]
	v_pk_add_f32 v[226:227], v[150:151], v[226:227]
	v_mfma_f32_16x16x32_bf16 v[64:67], v[192:195], v[96:99], v[64:67]
	v_pk_add_f32 v[226:227], v[148:149], v[226:227]
	s_waitcnt lgkmcnt(3)
	v_mfma_f32_16x16x32_bf16 v[92:95], v[196:199], v[168:171], v[92:95]
	v_pk_add_f32 v[226:227], v[146:147], v[226:227]
	v_mfma_f32_16x16x32_bf16 v[76:79], v[196:199], v[212:215], v[88:91]
	v_pk_add_f32 v[226:227], v[126:127], v[226:227]
	s_waitcnt lgkmcnt(2)
	v_mfma_f32_16x16x32_bf16 v[88:91], v[200:203], v[168:171], v[84:87]
	v_pk_add_f32 v[226:227], v[124:125], v[226:227]
	v_mfma_f32_16x16x32_bf16 v[72:75], v[200:203], v[212:215], v[80:83]
	v_pk_add_f32 v[226:227], v[122:123], v[226:227]
	s_waitcnt lgkmcnt(1)
	v_mfma_f32_16x16x32_bf16 v[84:87], v[204:207], v[168:171], v[100:103]
	v_pk_add_f32 v[226:227], v[120:121], v[226:227]
	v_mfma_f32_16x16x32_bf16 v[68:71], v[204:207], v[212:215], v[104:107]
	v_pk_add_f32 v[226:227], v[118:119], v[226:227]
	s_waitcnt lgkmcnt(0)
	v_mfma_f32_16x16x32_bf16 v[80:83], v[208:211], v[168:171], v[108:111]
	v_pk_add_f32 v[226:227], v[116:117], v[226:227]
	v_mfma_f32_16x16x32_bf16 v[64:67], v[208:211], v[212:215], v[64:67]
	v_pk_add_f32 v[226:227], v[112:113], v[226:227]
	s_setprio 0
	v_pk_add_f32 v[144:145], v[144:145], v[226:227]
	s_andn2_b64 vcc, exec, s[50:51]
	s_cbranch_vccnz .LBB0_375
	ds_write_b128 v179, v[24:27]
	ds_write_b128 v180, v[28:31]
	ds_write_b128 v181, v[32:35]
	ds_write_b128 v182, v[36:39] offset:16384
	ds_write_b128 v183, v[40:43] offset:16384
	s_branch .LBB0_375
